# attention tile loop: every 8-byte instruction placed on an 8-byte boundary (e32 to e64 promotions and a few s_nop 0), otherwise identical to the previous version
# speedup vs baseline: 1.0125x; 1.0125x over previous
; __device__ __forceinline__ void qkt(f32x16& p0, f32x16& p1, const char* Ks, const bf16x8* qr, int r32, int hi) {
;     p0 = f32x16{}; p1 = f32x16{};
; #pragma unroll
;     for (int d0 = 0; d0 < 6; ++d0) { const int cb = (d0 * 16 + hi * 8) * 2;
;         bf16x8 b0 = *reinterpret_cast<const bf16x8*>(Ks + KSWZ(r32, cb));
;         bf16x8 b1 = *reinterpret_cast<const bf16x8*>(Ks + KSWZ(32 + r32, cb));
;         p0 = __builtin_amdgcn_mfma_f32_32x32x16_bf16(b0, qr[d0], p0, 0, 0, 0);
;         p1 = __builtin_amdgcn_mfma_f32_32x32x16_bf16(b1, qr[d0], p1, 0, 0, 0); }
; }
.LA_swp:
	v_add_u32_e32 v247, 0x20000, v243
	global_load_dwordx4 v[228:231], v243, s[28:29]
	global_load_dwordx4 v[130:133], v247, s[28:29]
	global_load_dwordx4 v[248:251], v244, s[44:45]
	s_add_u32 s28, s28, 0x40000
	s_addc_u32 s29, s29, 0
	s_add_u32 s44, s44, 0x1000
	s_addc_u32 s45, s45, 0
	v_mov_b32_e32 v141, 0xf149f2ca
	v_mov_b32_e32 v254, 0
	v_mov_b32_e32 v64, 0
	v_mov_b32_e32 v0, 0
	v_mov_b32_e32 v1, 0
	v_mov_b32_e32 v2, 0
	v_mov_b32_e32 v3, 0
	v_mov_b32_e32 v4, 0
	v_mov_b32_e32 v5, 0
	v_mov_b32_e32 v6, 0
	v_mov_b32_e32 v7, 0
	v_mov_b32_e32 v8, 0
	v_mov_b32_e32 v9, 0
	v_mov_b32_e32 v10, 0
	v_mov_b32_e32 v11, 0
	v_mov_b32_e32 v12, 0
	v_mov_b32_e32 v13, 0
	v_mov_b32_e32 v14, 0
	v_mov_b32_e32 v15, 0
	v_mov_b32_e32 v16, 0
	v_mov_b32_e32 v17, 0
	v_mov_b32_e32 v18, 0
	v_mov_b32_e32 v19, 0
	v_mov_b32_e32 v20, 0
	v_mov_b32_e32 v21, 0
	v_mov_b32_e32 v22, 0
	v_mov_b32_e32 v23, 0
	v_mov_b32_e32 v24, 0
	v_mov_b32_e32 v25, 0
	v_mov_b32_e32 v26, 0
	v_mov_b32_e32 v27, 0
	v_mov_b32_e32 v28, 0
	v_mov_b32_e32 v29, 0
	v_mov_b32_e32 v30, 0
	v_mov_b32_e32 v31, 0
	v_mov_b32_e32 v139, 0xf149f2ca
	v_mov_b32_e32 v255, 0
	v_mov_b32_e32 v134, 0
	v_mov_b32_e32 v32, 0
	v_mov_b32_e32 v33, 0
	v_mov_b32_e32 v34, 0
	v_mov_b32_e32 v35, 0
	v_mov_b32_e32 v36, 0
	v_mov_b32_e32 v37, 0
	v_mov_b32_e32 v38, 0
	v_mov_b32_e32 v39, 0
	v_mov_b32_e32 v40, 0
	v_mov_b32_e32 v41, 0
	v_mov_b32_e32 v42, 0
	v_mov_b32_e32 v43, 0
	v_mov_b32_e32 v44, 0
	v_mov_b32_e32 v45, 0
	v_mov_b32_e32 v46, 0
	v_mov_b32_e32 v47, 0
	v_mov_b32_e32 v48, 0
	v_mov_b32_e32 v49, 0
	v_mov_b32_e32 v50, 0
	v_mov_b32_e32 v51, 0
	v_mov_b32_e32 v52, 0
	v_mov_b32_e32 v53, 0
	v_mov_b32_e32 v54, 0
	v_mov_b32_e32 v55, 0
	v_mov_b32_e32 v56, 0
	v_mov_b32_e32 v57, 0
	v_mov_b32_e32 v58, 0
	v_mov_b32_e32 v59, 0
	v_mov_b32_e32 v60, 0
	v_mov_b32_e32 v61, 0
	v_mov_b32_e32 v62, 0
	v_mov_b32_e32 v63, 0
	s_waitcnt lgkmcnt(0)
	s_barrier
	s_nop 0
.LA_loop:
	v_add_u32_e64 v247, s18, v236
	ds_read_b128 v[212:215], v247 offset:49152
	ds_read_b128 v[216:219], v247 offset:57344
	v_add_u32_e64 v247, s18, v237
	ds_read_b128 v[220:223], v247 offset:49152
	ds_read_b128 v[224:227], v247 offset:57344
	s_waitcnt lgkmcnt(2)
	s_nop 0
	v_mfma_f32_32x32x16_bf16 v[66:81], v[212:215], v[142:145], 0
	v_mfma_f32_32x32x16_bf16 v[82:97], v[216:219], v[142:145], 0
	v_mfma_f32_32x32x16_bf16 v[98:113], v[212:215], v[166:169], 0
	v_mfma_f32_32x32x16_bf16 v[114:129], v[216:219], v[166:169], 0
	v_add_u32_e64 v247, s18, v238
	ds_read_b128 v[212:215], v247 offset:49152
	ds_read_b128 v[216:219], v247 offset:57344
	s_waitcnt lgkmcnt(2)
	s_nop 0
	v_mfma_f32_32x32x16_bf16 v[66:81], v[220:223], v[146:149], v[66:81]
	v_mfma_f32_32x32x16_bf16 v[82:97], v[224:227], v[146:149], v[82:97]
	v_mfma_f32_32x32x16_bf16 v[98:113], v[220:223], v[170:173], v[98:113]
	v_mfma_f32_32x32x16_bf16 v[114:129], v[224:227], v[170:173], v[114:129]
	v_add_u32_e64 v247, s18, v239
	ds_read_b128 v[220:223], v247 offset:49152
	ds_read_b128 v[224:227], v247 offset:57344
	s_waitcnt lgkmcnt(2)
	s_nop 0
	v_mfma_f32_32x32x16_bf16 v[66:81], v[212:215], v[150:153], v[66:81]
	v_mfma_f32_32x32x16_bf16 v[82:97], v[216:219], v[150:153], v[82:97]
	v_mfma_f32_32x32x16_bf16 v[98:113], v[212:215], v[174:177], v[98:113]
	v_mfma_f32_32x32x16_bf16 v[114:129], v[216:219], v[174:177], v[114:129]
	v_add_u32_e64 v247, s18, v236
	ds_read_b128 v[212:215], v247 offset:49280
	ds_read_b128 v[216:219], v247 offset:57472
	s_waitcnt lgkmcnt(2)
	s_nop 0
	v_mfma_f32_32x32x16_bf16 v[66:81], v[220:223], v[154:157], v[66:81]
	v_mfma_f32_32x32x16_bf16 v[82:97], v[224:227], v[154:157], v[82:97]
	v_mfma_f32_32x32x16_bf16 v[98:113], v[220:223], v[178:181], v[98:113]
	v_mfma_f32_32x32x16_bf16 v[114:129], v[224:227], v[178:181], v[114:129]
	v_add_u32_e64 v247, s18, v237
	ds_read_b128 v[220:223], v247 offset:49280
	ds_read_b128 v[224:227], v247 offset:57472
	s_waitcnt lgkmcnt(2)
	s_nop 0
	v_mfma_f32_32x32x16_bf16 v[66:81], v[212:215], v[158:161], v[66:81]
	v_mfma_f32_32x32x16_bf16 v[82:97], v[216:219], v[158:161], v[82:97]
	v_mfma_f32_32x32x16_bf16 v[98:113], v[212:215], v[182:185], v[98:113]
	v_mfma_f32_32x32x16_bf16 v[114:129], v[216:219], v[182:185], v[114:129]
	s_waitcnt lgkmcnt(0)
	s_nop 0
	v_mfma_f32_32x32x16_bf16 v[66:81], v[220:223], v[162:165], v[66:81]
	v_mfma_f32_32x32x16_bf16 v[82:97], v[224:227], v[162:165], v[82:97]
	v_mfma_f32_32x32x16_bf16 v[98:113], v[220:223], v[186:189], v[98:113]
	v_mfma_f32_32x32x16_bf16 v[114:129], v[224:227], v[186:189], v[114:129]
	s_cmp_gt_u32 s16, 62
	s_cbranch_scc1 .LA_nosw
	s_waitcnt vmcnt(0)
	v_add_u32_e32 v246, s19, v240
	v_add_u32_e64 v245, s19, v241
	ds_write_b128 v246, v[228:231]
	ds_write_b128 v245, v[130:133]
	s_cmp_eq_u64 s[2:3], 0
	s_cbranch_scc1 .LA_swl
	v_add_u32_e64 v245, s19, v242
	ds_write_b128 v245, v[248:251] offset:49152
.LA_swl:
	s_cmp_gt_u32 s16, 61
	s_cbranch_scc1 .LA_nosw
	v_add_u32_e32 v247, 0x20000, v243
	global_load_dwordx4 v[228:231], v243, s[28:29]
	global_load_dwordx4 v[130:133], v247, s[28:29]
	global_load_dwordx4 v[248:251], v244, s[44:45]
	s_add_u32 s28, s28, 0x40000
	s_addc_u32 s29, s29, 0
	s_nop 0
	s_add_u32 s44, s44, 0x1000
	s_addc_u32 s45, s45, 0
; __device__ __forceinline__ void partialSM(f32x16& p0, f32x16& p1, float& m_reg, float& mn, float& alpha) {
;     constexpr float Cc = SCALE * 1.4426950408889634f;
;     float pmax = p0[0];
; #pragma unroll
;     for (int r = 1; r < 16; ++r) pmax = fmaxf(pmax, p0[r]);
; #pragma unroll
;     for (int r = 0; r < 16; ++r) pmax = fmaxf(pmax, p1[r]);
;     { auto rr = __builtin_amdgcn_permlane32_swap(__float_as_uint(pmax), __float_as_uint(pmax), false, false);
;       pmax = fmaxf(__uint_as_float(rr[0]), __uint_as_float(rr[1])); }
;     if (__builtin_expect(__all(pmax - m_reg <= THR / SCALE), 1)) { mn = m_reg; alpha = 1.f; }
;     else { mn = fmaxf(m_reg, pmax); alpha = __builtin_amdgcn_exp2f((m_reg - mn) * Cc); m_reg = mn; }
;     const float mnC = -mn * Cc;
;     { typedef float f32x2 __attribute__((ext_vector_type(2))); const f32x2 c2 = {Cc, Cc}, m2 = {mnC, mnC};
; #pragma unroll
;       for (int r = 0; r < 16; r += 2) { f32x2 t = {p0[r], p0[r + 1]}; t = __builtin_elementwise_fma(t, c2, m2); p0[r] = t.x; p0[r + 1] = t.y; }
; #pragma unroll
;       for (int r = 0; r < 16; r += 2) { f32x2 t = {p1[r], p1[r + 1]}; t = __builtin_elementwise_fma(t, c2, m2); p1[r] = t.x; p1[r + 1] = t.y; } }
; #pragma unroll
;     for (int r = 0; r < 16; ++r) p0[r] = __builtin_amdgcn_exp2f(p0[r]);
; }
; __device__ __forceinline__ void finishSM(f32x16& p0, f32x16& p1, float alpha, float& l_reg, bf16x8& pa0, bf16x8& pa1, bf16x8& pa2, bf16x8& pa3) {
; #pragma unroll
;     for (int r = 0; r < 16; ++r) p1[r] = __builtin_amdgcn_exp2f(p1[r]);
;     float ps;
;     { typedef float f32x2 __attribute__((ext_vector_type(2))); f32x2 s0 = {p0[0], p0[1]}, s1 = {p1[0], p1[1]};
; #pragma unroll
;       for (int r = 2; r < 16; r += 2) { s0 += (f32x2){p0[r], p0[r + 1]}; s1 += (f32x2){p1[r], p1[r + 1]}; }
;       s0 += s1; ps = s0.x + s0.y; }
;     { auto rr = __builtin_amdgcn_permlane32_swap(__float_as_uint(ps), __float_as_uint(ps), false, false);
;       ps = __uint_as_float(rr[0]) + __uint_as_float(rr[1]); }
;     l_reg = l_reg * alpha + ps;
;     ...
;     PK4(p0, 0, pa0); PK4(p0, 8, pa1); PK4(p1, 0, pa2); PK4(p1, 8, pa3);
;     ...
; }
.LA_nosw:
	v_add_u32_e32 v202, s18, v235
	v_max_f32_e32 v212, v66, v67
	v_max_f32_e32 v213, v82, v83
	v_max3_f32 v212, v212, v68, v69
	v_max3_f32 v213, v213, v84, v85
	v_max3_f32 v212, v212, v70, v71
	v_max3_f32 v213, v213, v86, v87
	v_max3_f32 v212, v212, v72, v73
	v_max3_f32 v213, v213, v88, v89
	v_max3_f32 v212, v212, v74, v75
	v_max3_f32 v213, v213, v90, v91
	v_max3_f32 v212, v212, v76, v77
	v_max3_f32 v213, v213, v92, v93
	v_max3_f32 v212, v212, v78, v79
	v_max3_f32 v213, v213, v94, v95
	v_max3_f32 v212, v212, v80, v81
	v_max3_f32 v213, v213, v96, v97
	v_max_f32_e32 v212, v212, v213
	v_mov_b32_e32 v213, v212
	s_nop 1
	v_permlane32_swap_b32_e32 v212, v213
	v_max_f32_e32 v212, v212, v213
	v_sub_f32_e32 v214, v212, v141
	v_cmp_ge_f32_e32 vcc, s67, v214
	v_max_f32_e32 v212, v141, v212
	v_sub_f32_e64 v214, v141, v212
	v_mul_f32_e32 v214, 0x3e16c740, v214
	v_exp_f32_e64 v215, v214
	s_cmp_eq_u64 vcc, exec
	s_cselect_b64 s[58:59], -1, 0
	v_cndmask_b32_e64 v141, v212, v141, s[58:59]
	v_cndmask_b32_e64 v215, v215, 1.0, s[58:59]
	v_mul_f32_e32 v216, 0xbe16c740, v141
	v_fma_f32 v66, v66, s52, v216
	v_fma_f32 v67, v67, s52, v216
	v_fma_f32 v68, v68, s52, v216
	v_fma_f32 v69, v69, s52, v216
	v_fma_f32 v70, v70, s52, v216
	v_fma_f32 v71, v71, s52, v216
	v_fma_f32 v72, v72, s52, v216
	v_fma_f32 v73, v73, s52, v216
	v_fma_f32 v74, v74, s52, v216
	v_fma_f32 v75, v75, s52, v216
	v_fma_f32 v76, v76, s52, v216
	v_fma_f32 v77, v77, s52, v216
	v_fma_f32 v78, v78, s52, v216
	v_fma_f32 v79, v79, s52, v216
	v_fma_f32 v80, v80, s52, v216
	v_fma_f32 v81, v81, s52, v216
	v_fma_f32 v82, v82, s52, v216
	v_fma_f32 v83, v83, s52, v216
	v_fma_f32 v84, v84, s52, v216
	v_fma_f32 v85, v85, s52, v216
	v_fma_f32 v86, v86, s52, v216
	v_fma_f32 v87, v87, s52, v216
	v_fma_f32 v88, v88, s52, v216
	v_fma_f32 v89, v89, s52, v216
	v_fma_f32 v90, v90, s52, v216
	v_fma_f32 v91, v91, s52, v216
	v_fma_f32 v92, v92, s52, v216
	v_fma_f32 v93, v93, s52, v216
	v_fma_f32 v94, v94, s52, v216
	v_fma_f32 v95, v95, s52, v216
	v_fma_f32 v96, v96, s52, v216
	v_fma_f32 v97, v97, s52, v216
	v_exp_f32_e32 v66, v66
	v_exp_f32_e32 v67, v67
	v_exp_f32_e32 v68, v68
	v_exp_f32_e32 v69, v69
	v_exp_f32_e32 v70, v70
	v_exp_f32_e32 v71, v71
	v_exp_f32_e32 v72, v72
	v_exp_f32_e32 v73, v73
	v_exp_f32_e32 v74, v74
	v_exp_f32_e32 v75, v75
	v_exp_f32_e32 v76, v76
	v_exp_f32_e32 v77, v77
	v_exp_f32_e32 v78, v78
	v_exp_f32_e32 v79, v79
	v_exp_f32_e32 v80, v80
	v_exp_f32_e32 v81, v81
	v_exp_f32_e32 v82, v82
	v_exp_f32_e32 v83, v83
	v_exp_f32_e32 v84, v84
	v_exp_f32_e32 v85, v85
	v_exp_f32_e32 v86, v86
	v_exp_f32_e32 v87, v87
	v_exp_f32_e32 v88, v88
	v_exp_f32_e32 v89, v89
	v_exp_f32_e32 v90, v90
	v_exp_f32_e32 v91, v91
	v_exp_f32_e32 v92, v92
	v_exp_f32_e32 v93, v93
	v_exp_f32_e32 v94, v94
	v_exp_f32_e32 v95, v95
	v_exp_f32_e32 v96, v96
	v_exp_f32_e32 v97, v97
	v_add_f32_e32 v212, v66, v68
	v_add_f32_e32 v213, v67, v69
	v_add_f32_e32 v212, v70, v212
	v_add_f32_e32 v213, v71, v213
	v_add_f32_e32 v212, v72, v212
	v_add_f32_e32 v213, v73, v213
	v_add_f32_e32 v212, v74, v212
	v_add_f32_e32 v213, v75, v213
	v_add_f32_e32 v212, v76, v212
	v_add_f32_e32 v213, v77, v213
	v_add_f32_e32 v212, v78, v212
	v_add_f32_e32 v213, v79, v213
	v_add_f32_e32 v212, v80, v212
	v_add_f32_e32 v213, v81, v213
	v_add_f32_e32 v212, v82, v212
	v_add_f32_e32 v213, v83, v213
	v_add_f32_e32 v212, v84, v212
	v_add_f32_e32 v213, v85, v213
	v_add_f32_e32 v212, v86, v212
	v_add_f32_e32 v213, v87, v213
	v_add_f32_e32 v212, v88, v212
	v_add_f32_e32 v213, v89, v213
	v_add_f32_e32 v212, v90, v212
	v_add_f32_e32 v213, v91, v213
	v_add_f32_e32 v212, v92, v212
	v_add_f32_e32 v213, v93, v213
	v_add_f32_e32 v212, v94, v212
	v_add_f32_e32 v213, v95, v213
	v_add_f32_e32 v212, v96, v212
	v_add_f32_e32 v213, v97, v213
	v_add_f32_e64 v212, v212, v213
	v_fma_f32 v254, v254, v215, v212
	v_cvt_pk_bf16_f32 v66, v66, v67
	v_cvt_pk_bf16_f32 v67, v68, v69
	v_cvt_pk_bf16_f32 v68, v70, v71
	v_cvt_pk_bf16_f32 v69, v72, v73
	v_cvt_pk_bf16_f32 v70, v74, v75
	v_cvt_pk_bf16_f32 v71, v76, v77
	v_cvt_pk_bf16_f32 v72, v78, v79
	v_cvt_pk_bf16_f32 v73, v80, v81
	v_cvt_pk_bf16_f32 v82, v82, v83
	v_cvt_pk_bf16_f32 v83, v84, v85
	v_cvt_pk_bf16_f32 v84, v86, v87
	v_cvt_pk_bf16_f32 v85, v88, v89
	v_cvt_pk_bf16_f32 v86, v90, v91
	v_cvt_pk_bf16_f32 v87, v92, v93
	v_cvt_pk_bf16_f32 v88, v94, v95
	v_cvt_pk_bf16_f32 v89, v96, v97
	v_permlane32_swap_b32_e32 v66, v68
	v_permlane32_swap_b32_e32 v67, v69
	v_permlane32_swap_b32_e32 v70, v72
	v_permlane32_swap_b32_e32 v71, v73
	v_permlane32_swap_b32_e32 v82, v84
	v_permlane32_swap_b32_e32 v83, v85
	v_permlane32_swap_b32_e32 v86, v88
	v_permlane32_swap_b32_e32 v87, v89
	v_cmp_gt_f32_e32 vcc, 1.0, v215
	s_cbranch_vccz .LA_rs0
	s_and_saveexec_b64 s[60:61], s[4:5]
	s_nop 0
	ds_write_b32 v234, v215 offset:128
	s_or_b64 exec, exec, s[60:61]
	s_waitcnt lgkmcnt(0)
	v_add_u32_e64 v245, v232, v233
	ds_read_b128 v[220:223], v245 offset:224
	ds_read_b128 v[224:227], v245 offset:192
	ds_read_b128 v[216:219], v245 offset:160
	ds_read_b128 v[212:215], v245 offset:128
	s_waitcnt lgkmcnt(0)
	s_waitcnt lgkmcnt(3)
	v_mul_f32_e32 v12, v12, v220
	v_mul_f32_e32 v13, v13, v221
	v_mul_f32_e32 v14, v14, v222
	v_mul_f32_e32 v15, v15, v223
	s_waitcnt lgkmcnt(2)
	v_mul_f32_e32 v8, v8, v224
	v_mul_f32_e32 v9, v9, v225
	v_mul_f32_e32 v10, v10, v226
	v_mul_f32_e32 v11, v11, v227
	s_waitcnt lgkmcnt(1)
	v_mul_f32_e32 v4, v4, v216
	v_mul_f32_e32 v5, v5, v217
	v_mul_f32_e32 v6, v6, v218
	v_mul_f32_e32 v7, v7, v219
	s_waitcnt lgkmcnt(0)
	v_mul_f32_e32 v0, v0, v212
	v_mul_f32_e32 v1, v1, v213
	v_mul_f32_e32 v2, v2, v214
	v_mul_f32_e32 v3, v3, v215
	v_mul_f32_e32 v28, v28, v220
	v_mul_f32_e32 v29, v29, v221
	v_mul_f32_e32 v30, v30, v222
	v_mul_f32_e32 v31, v31, v223
	v_mul_f32_e32 v24, v24, v224
	v_mul_f32_e32 v25, v25, v225
	v_mul_f32_e32 v26, v26, v226
	v_mul_f32_e32 v27, v27, v227
	v_mul_f32_e32 v20, v20, v216
	v_mul_f32_e32 v21, v21, v217
	v_mul_f32_e32 v22, v22, v218
	v_mul_f32_e32 v23, v23, v219
	v_mul_f32_e32 v16, v16, v212
	v_mul_f32_e32 v17, v17, v213
	v_mul_f32_e32 v18, v18, v214
	v_mul_f32_e64 v19, v19, v215

; __device__ __forceinline__ void partialSM(f32x16& p0, f32x16& p1, float& m_reg, float& mn, float& alpha) {
;     constexpr float Cc = SCALE * 1.4426950408889634f;
;     float pmax = p0[0];
; #pragma unroll
;     for (int r = 1; r < 16; ++r) pmax = fmaxf(pmax, p0[r]);
; #pragma unroll
;     for (int r = 0; r < 16; ++r) pmax = fmaxf(pmax, p1[r]);
;     { auto rr = __builtin_amdgcn_permlane32_swap(__float_as_uint(pmax), __float_as_uint(pmax), false, false);
;       pmax = fmaxf(__uint_as_float(rr[0]), __uint_as_float(rr[1])); }
;     if (__builtin_expect(__all(pmax - m_reg <= THR / SCALE), 1)) { mn = m_reg; alpha = 1.f; }
;     else { mn = fmaxf(m_reg, pmax); alpha = __builtin_amdgcn_exp2f((m_reg - mn) * Cc); m_reg = mn; }
;     const float mnC = -mn * Cc;
;     { typedef float f32x2 __attribute__((ext_vector_type(2))); const f32x2 c2 = {Cc, Cc}, m2 = {mnC, mnC};
; #pragma unroll
;       for (int r = 0; r < 16; r += 2) { f32x2 t = {p0[r], p0[r + 1]}; t = __builtin_elementwise_fma(t, c2, m2); p0[r] = t.x; p0[r + 1] = t.y; }
; #pragma unroll
;       for (int r = 0; r < 16; r += 2) { f32x2 t = {p1[r], p1[r + 1]}; t = __builtin_elementwise_fma(t, c2, m2); p1[r] = t.x; p1[r + 1] = t.y; } }
; #pragma unroll
;     for (int r = 0; r < 16; ++r) p0[r] = __builtin_amdgcn_exp2f(p0[r]);
; }
; __device__ __forceinline__ void finishSM(f32x16& p0, f32x16& p1, float alpha, float& l_reg, bf16x8& pa0, bf16x8& pa1, bf16x8& pa2, bf16x8& pa3) {
; #pragma unroll
;     for (int r = 0; r < 16; ++r) p1[r] = __builtin_amdgcn_exp2f(p1[r]);
;     float ps;
;     { typedef float f32x2 __attribute__((ext_vector_type(2))); f32x2 s0 = {p0[0], p0[1]}, s1 = {p1[0], p1[1]};
; #pragma unroll
;       for (int r = 2; r < 16; r += 2) { s0 += (f32x2){p0[r], p0[r + 1]}; s1 += (f32x2){p1[r], p1[r + 1]}; }
;       s0 += s1; ps = s0.x + s0.y; }
;     { auto rr = __builtin_amdgcn_permlane32_swap(__float_as_uint(ps), __float_as_uint(ps), false, false);
;       ps = __uint_as_float(rr[0]) + __uint_as_float(rr[1]); }
;     l_reg = l_reg * alpha + ps;
;     ...
;     PK4(p0, 0, pa0); PK4(p0, 8, pa1); PK4(p1, 0, pa2); PK4(p1, 8, pa3);
;     ...
; }
.LA_g1b:
	ds_read_b64_tr_b16 v[74:75], v202 offset:0
	ds_read_b64_tr_b16 v[76:77], v202 offset:2048
	ds_read_b64_tr_b16 v[78:79], v202 offset:4096
	ds_read_b64_tr_b16 v[80:81], v202 offset:6144
	ds_read_b64_tr_b16 v[90:91], v202 offset:8192
	ds_read_b64_tr_b16 v[92:93], v202 offset:10240
	ds_read_b64_tr_b16 v[94:95], v202 offset:12288
	ds_read_b64_tr_b16 v[96:97], v202 offset:14336
	v_max_f32_e32 v212, v98, v99
	v_max_f32_e32 v213, v114, v115
	v_max3_f32 v212, v212, v100, v101
	v_max3_f32 v213, v213, v116, v117
	v_max3_f32 v212, v212, v102, v103
	v_max3_f32 v213, v213, v118, v119
	v_max3_f32 v212, v212, v104, v105
	v_max3_f32 v213, v213, v120, v121
	v_max3_f32 v212, v212, v106, v107
	v_max3_f32 v213, v213, v122, v123
	v_max3_f32 v212, v212, v108, v109
	v_max3_f32 v213, v213, v124, v125
	v_max3_f32 v212, v212, v110, v111
	v_max3_f32 v213, v213, v126, v127
	v_max3_f32 v212, v212, v112, v113
	v_max3_f32 v213, v213, v128, v129
	v_max_f32_e32 v212, v212, v213
	v_mov_b32_e32 v213, v212
	s_nop 1
	v_permlane32_swap_b32_e32 v212, v213
	v_max_f32_e32 v212, v212, v213
	v_sub_f32_e32 v214, v212, v139
	v_cmp_ge_f32_e32 vcc, s67, v214
	v_max_f32_e32 v212, v139, v212
	v_sub_f32_e64 v214, v139, v212
	v_mul_f32_e32 v214, 0x3e16c740, v214
	v_exp_f32_e64 v215, v214
	s_cmp_eq_u64 vcc, exec
	s_cselect_b64 s[58:59], -1, 0
	v_cndmask_b32_e64 v139, v212, v139, s[58:59]
	v_cndmask_b32_e64 v215, v215, 1.0, s[58:59]
	v_mul_f32_e32 v216, 0xbe16c740, v139
	v_fma_f32 v98, v98, s52, v216
	v_fma_f32 v99, v99, s52, v216
	v_fma_f32 v100, v100, s52, v216
	v_fma_f32 v101, v101, s52, v216
	v_fma_f32 v102, v102, s52, v216
	v_fma_f32 v103, v103, s52, v216
	v_fma_f32 v104, v104, s52, v216
	v_fma_f32 v105, v105, s52, v216
	v_fma_f32 v106, v106, s52, v216
	v_fma_f32 v107, v107, s52, v216
	v_fma_f32 v108, v108, s52, v216
	v_fma_f32 v109, v109, s52, v216
	v_fma_f32 v110, v110, s52, v216
	v_fma_f32 v111, v111, s52, v216
	v_fma_f32 v112, v112, s52, v216
	v_fma_f32 v113, v113, s52, v216
	v_fma_f32 v114, v114, s52, v216
	v_fma_f32 v115, v115, s52, v216
	v_fma_f32 v116, v116, s52, v216
	v_fma_f32 v117, v117, s52, v216
	v_fma_f32 v118, v118, s52, v216
	v_fma_f32 v119, v119, s52, v216
	v_fma_f32 v120, v120, s52, v216
	v_fma_f32 v121, v121, s52, v216
	v_fma_f32 v122, v122, s52, v216
	v_fma_f32 v123, v123, s52, v216
	v_fma_f32 v124, v124, s52, v216
	v_fma_f32 v125, v125, s52, v216
	v_fma_f32 v126, v126, s52, v216
	v_fma_f32 v127, v127, s52, v216
	v_fma_f32 v128, v128, s52, v216
	v_fma_f32 v129, v129, s52, v216
	v_exp_f32_e32 v98, v98
	v_exp_f32_e32 v99, v99
	v_exp_f32_e32 v100, v100
	v_exp_f32_e32 v101, v101
	v_exp_f32_e32 v102, v102
	v_exp_f32_e32 v103, v103
	v_exp_f32_e32 v104, v104
	v_exp_f32_e32 v105, v105
	v_exp_f32_e32 v106, v106
	v_exp_f32_e32 v107, v107
	v_exp_f32_e32 v108, v108
	v_exp_f32_e32 v109, v109
	v_exp_f32_e32 v110, v110
	v_exp_f32_e32 v111, v111
	v_exp_f32_e32 v112, v112
	v_exp_f32_e32 v113, v113
	v_exp_f32_e32 v114, v114
	v_exp_f32_e32 v115, v115
	v_exp_f32_e32 v116, v116
	v_exp_f32_e32 v117, v117
	v_exp_f32_e32 v118, v118
	v_exp_f32_e32 v119, v119
	v_exp_f32_e32 v120, v120
	v_exp_f32_e32 v121, v121
	v_exp_f32_e32 v122, v122
	v_exp_f32_e32 v123, v123
	v_exp_f32_e32 v124, v124
	v_exp_f32_e32 v125, v125
	v_exp_f32_e32 v126, v126
	v_exp_f32_e32 v127, v127
	v_exp_f32_e32 v128, v128
	v_exp_f32_e32 v129, v129
	v_add_f32_e32 v212, v98, v100
	v_add_f32_e32 v213, v99, v101
	v_add_f32_e32 v212, v102, v212
	v_add_f32_e32 v213, v103, v213
	v_add_f32_e32 v212, v104, v212
	v_add_f32_e32 v213, v105, v213
	v_add_f32_e32 v212, v106, v212
	v_add_f32_e32 v213, v107, v213
	v_add_f32_e32 v212, v108, v212
	v_add_f32_e32 v213, v109, v213
	v_add_f32_e32 v212, v110, v212
	v_add_f32_e32 v213, v111, v213
	v_add_f32_e32 v212, v112, v212
	v_add_f32_e32 v213, v113, v213
	v_add_f32_e32 v212, v114, v212
	v_add_f32_e32 v213, v115, v213
	v_add_f32_e32 v212, v116, v212
	v_add_f32_e32 v213, v117, v213
	v_add_f32_e32 v212, v118, v212
	v_add_f32_e32 v213, v119, v213
	v_add_f32_e32 v212, v120, v212
	v_add_f32_e32 v213, v121, v213
	v_add_f32_e32 v212, v122, v212
	v_add_f32_e32 v213, v123, v213
	v_add_f32_e32 v212, v124, v212
	v_add_f32_e32 v213, v125, v213
	v_add_f32_e32 v212, v126, v212
	v_add_f32_e32 v213, v127, v213
	v_add_f32_e32 v212, v128, v212
	v_add_f32_e32 v213, v129, v213
	v_add_f32_e64 v212, v212, v213
	v_fma_f32 v255, v255, v215, v212
	v_cvt_pk_bf16_f32 v98, v98, v99
	v_cvt_pk_bf16_f32 v99, v100, v101
	v_cvt_pk_bf16_f32 v100, v102, v103
	v_cvt_pk_bf16_f32 v101, v104, v105
	v_cvt_pk_bf16_f32 v102, v106, v107
	v_cvt_pk_bf16_f32 v103, v108, v109
	v_cvt_pk_bf16_f32 v104, v110, v111
	v_cvt_pk_bf16_f32 v105, v112, v113
	v_cvt_pk_bf16_f32 v114, v114, v115
	v_cvt_pk_bf16_f32 v115, v116, v117
	v_cvt_pk_bf16_f32 v116, v118, v119
	v_cvt_pk_bf16_f32 v117, v120, v121
	v_cvt_pk_bf16_f32 v118, v122, v123
	v_cvt_pk_bf16_f32 v119, v124, v125
	v_cvt_pk_bf16_f32 v120, v126, v127
	v_cvt_pk_bf16_f32 v121, v128, v129
	v_permlane32_swap_b32_e32 v98, v100
	v_permlane32_swap_b32_e32 v99, v101
	v_permlane32_swap_b32_e32 v102, v104
	v_permlane32_swap_b32_e32 v103, v105
	v_permlane32_swap_b32_e32 v114, v116
	v_permlane32_swap_b32_e32 v115, v117
	v_permlane32_swap_b32_e32 v118, v120
	v_permlane32_swap_b32_e32 v119, v121
	v_cmp_gt_f32_e32 vcc, 1.0, v215
	s_cbranch_vccz .LA_rs1
	s_and_saveexec_b64 s[60:61], s[4:5]
	s_nop 0
	ds_write_b32 v234, v215 offset:128
	s_or_b64 exec, exec, s[60:61]
	s_waitcnt lgkmcnt(0)
	v_add_u32_e64 v245, v232, v233
	ds_read_b128 v[220:223], v245 offset:224
	ds_read_b128 v[224:227], v245 offset:192
	ds_read_b128 v[216:219], v245 offset:160
	ds_read_b128 v[212:215], v245 offset:128
	s_waitcnt lgkmcnt(0)
	s_waitcnt lgkmcnt(3)
	v_mul_f32_e32 v44, v44, v220
	v_mul_f32_e32 v45, v45, v221
	v_mul_f32_e32 v46, v46, v222
	v_mul_f32_e32 v47, v47, v223
	s_waitcnt lgkmcnt(2)
	v_mul_f32_e32 v40, v40, v224
	v_mul_f32_e32 v41, v41, v225
	v_mul_f32_e32 v42, v42, v226
	v_mul_f32_e32 v43, v43, v227
	s_waitcnt lgkmcnt(1)
	v_mul_f32_e32 v36, v36, v216
	v_mul_f32_e32 v37, v37, v217
	v_mul_f32_e32 v38, v38, v218
	v_mul_f32_e32 v39, v39, v219
	s_waitcnt lgkmcnt(0)
	v_mul_f32_e32 v32, v32, v212
	v_mul_f32_e32 v33, v33, v213
	v_mul_f32_e32 v34, v34, v214
	v_mul_f32_e32 v35, v35, v215
	v_mul_f32_e32 v60, v60, v220
	v_mul_f32_e32 v61, v61, v221
	v_mul_f32_e32 v62, v62, v222
	v_mul_f32_e32 v63, v63, v223
	v_mul_f32_e32 v56, v56, v224
	v_mul_f32_e32 v57, v57, v225
	v_mul_f32_e32 v58, v58, v226
	v_mul_f32_e32 v59, v59, v227
	v_mul_f32_e32 v52, v52, v216
	v_mul_f32_e32 v53, v53, v217
	v_mul_f32_e32 v54, v54, v218
	v_mul_f32_e32 v55, v55, v219
	v_mul_f32_e32 v48, v48, v212
	v_mul_f32_e32 v49, v49, v213
	v_mul_f32_e32 v50, v50, v214
	v_mul_f32_e64 v51, v51, v215
; #define SBAR() __builtin_amdgcn_sched_barrier(0)
; template <int D0> __device__ __forceinline__ void pv_one(f32x16& od, int vb, bf16x8 pa0, bf16x8 pa1, bf16x8 pa2, bf16x8 pa3) {
;     const s16x4 l0 = tr_read<v_rd_off(D0, 0, 0)>(vb), h0 = tr_read<v_rd_off(D0, 0, 1)>(vb), l1 = tr_read<v_rd_off(D0, 1, 0)>(vb), h1 = tr_read<v_rd_off(D0, 1, 1)>(vb);
;     const s16x4 l2 = tr_read<v_rd_off(D0, 2, 0)>(vb), h2 = tr_read<v_rd_off(D0, 2, 1)>(vb), l3 = tr_read<v_rd_off(D0, 3, 0)>(vb), h3 = tr_read<v_rd_off(D0, 3, 1)>(vb);
;     asm volatile("s_waitcnt lgkmcnt(0)" ::: "memory"); SBAR();
;     ...
;     od = __builtin_amdgcn_mfma_f32_32x32x16_bf16(pa0, PK(l0, h0), od, 0, 0, 0);
;     od = __builtin_amdgcn_mfma_f32_32x32x16_bf16(pa1, PK(l1, h1), od, 0, 0, 0);
;     od = __builtin_amdgcn_mfma_f32_32x32x16_bf16(pa2, PK(l2, h2), od, 0, 0, 0);
;     od = __builtin_amdgcn_mfma_f32_32x32x16_bf16(pa3, PK(l3, h3), od, 0, 0, 0);
.LA_rs1:
	ds_read_b64_tr_b16 v[106:107], v202 offset:512
	ds_read_b64_tr_b16 v[108:109], v202 offset:2560
	ds_read_b64_tr_b16 v[110:111], v202 offset:4608
	ds_read_b64_tr_b16 v[112:113], v202 offset:6656
	ds_read_b64_tr_b16 v[122:123], v202 offset:8704
	ds_read_b64_tr_b16 v[124:125], v202 offset:10752
	ds_read_b64_tr_b16 v[126:127], v202 offset:12800
	ds_read_b64_tr_b16 v[128:129], v202 offset:14848
	s_waitcnt lgkmcnt(8)
	s_nop 0
	v_mfma_f32_32x32x16_bf16 v[0:15], v[66:69], v[74:77], v[0:15]
	v_mfma_f32_32x32x16_bf16 v[32:47], v[98:101], v[74:77], v[32:47]
	v_mfma_f32_32x32x16_bf16 v[0:15], v[70:73], v[78:81], v[0:15]
	v_mfma_f32_32x32x16_bf16 v[32:47], v[102:105], v[78:81], v[32:47]
	v_mfma_f32_32x32x16_bf16 v[0:15], v[82:85], v[90:93], v[0:15]
	v_mfma_f32_32x32x16_bf16 v[32:47], v[114:117], v[90:93], v[32:47]
	v_mfma_f32_32x32x16_bf16 v[0:15], v[86:89], v[94:97], v[0:15]
	v_mfma_f32_32x32x16_bf16 v[32:47], v[118:121], v[94:97], v[32:47]
	s_waitcnt lgkmcnt(6)
	s_nop 0
	v_mfma_f32_32x32x16_bf16 v[16:31], v[66:69], v[106:109], v[16:31]
	v_mfma_f32_32x32x16_bf16 v[48:63], v[98:101], v[106:109], v[48:63]
	s_waitcnt lgkmcnt(4)
	s_nop 0
	v_mfma_f32_32x32x16_bf16 v[16:31], v[70:73], v[110:113], v[16:31]
	v_mfma_f32_32x32x16_bf16 v[48:63], v[102:105], v[110:113], v[48:63]
	s_waitcnt lgkmcnt(2)
	s_nop 0
	v_mfma_f32_32x32x16_bf16 v[16:31], v[82:85], v[122:125], v[16:31]
	v_mfma_f32_32x32x16_bf16 v[48:63], v[114:117], v[122:125], v[48:63]
	s_waitcnt lgkmcnt(0)
	s_nop 0
	v_mfma_f32_32x32x16_bf16 v[16:31], v[86:89], v[126:129], v[16:31]
	v_mfma_f32_32x32x16_bf16 v[48:63], v[118:121], v[126:129], v[48:63]
	s_waitcnt lgkmcnt(0)
	s_cmp_eq_u64 s[2:3], 0
	s_cbranch_scc1 .LA_g0b
	s_barrier
